# kprio4 + DIFF and RET tile loops: LDS-DMA source addresses as scalar base + 32-bit lane offset (v_mul_u32_u24) instead of 64-bit v_mad_i64_i32 chains
# speedup vs baseline: 1.0015x; 1.0015x over previous
; template <int MODE>
; __device__ __forceinline__ void flash_unit(ArgsP A, int l, int b, int h, int qb, unsigned char* lds) {
;     ...
;     auto dma_tile = [&](int t) {
;         const int kr0 = rowbase + 64 * t;
;         const int slot = t % NBUF; const unsigned kb_ = lds0 + slot * KBYTES, vb_ = lds0 + NBUF * KBYTES + slot * VBYTES;
; #pragma unroll
;         for (int i = 0; i < NKI; ++i) { const int piece = wave + 8 * i, p = 64 * piece + lane, key = p / KCH, cs = p % KCH;
;             const int ch = cs ^ (MODE == 1 ? (key & 15) : ((key >> 1) & 7)); const bf16_t* src;
;             if (MODE == 0) src = (ch < 16) ? KVM + (size_t)(kr0 + key) * 1024 + 256 * h + 8 * ch : PROJ + (size_t)(kr0 + key) * INWP + C_KR + 8 * (ch - 16);
;             else if (MODE == 1) src = PROJ + (size_t)(kr0 + key) * INWP + C_DK + 128 * h + 8 * ch;
;             else src = PROJ + (size_t)(kr0 + key) * INWP + C_RK + 64 * h + 8 * ch;
;             glds16(src, (unsigned)__builtin_amdgcn_readfirstlane(kb_ + piece * 1024)); }
; #pragma unroll
;         for (int i = 0; i < 2; ++i) { const int piece = wave + 8 * i, p = 64 * piece + lane, st = p >> 5, key = 8 * (st >> 2) + ((p & 31) >> 2), col = 32 * (st & 3) + 8 * (p & 3); const bf16_t* src;
;             if (MODE == 0) src = KVM + (size_t)(kr0 + key) * 1024 + 256 * h + 128 + col;
;             else if (MODE == 1) src = PROJ + (size_t)(kr0 + key) * INWP + C_DV + 128 * h + col;
;             else src = PROJ + (size_t)(kr0 + key) * INWP + C_RV + 128 * h + col;
;             glds16(src, (unsigned)__builtin_amdgcn_readfirstlane(vb_ + piece * 1024)); }
;         if (MODE == 1) glds4((const int*)A->in[2] + rowbase + 64 * t + lane, (unsigned)__builtin_amdgcn_readfirstlane(lds0 + OFF_EXTRA + slot * 256));
;     };
;     ...
;         if (t + NBUF - 1 < ntile) dma_tile(t + NBUF - 1);
;         if (t <= tlast) {
.LBB0_779:
	s_and_b32 s8, s8, 3
	s_lshl_b32 s20, s8, 13
	s_lshl_b32 s21, s8, 14
	s_add_u32 s100, s4, s88
	s_addc_u32 s101, s5, s89
	v_add_u32_e32 v82, s10, v202
	v_mul_u32_u24_e32 v82, s35, v82
	v_lshl_add_u32 v82, v166, 1, v82
	v_add_u32_e32 v80, s10, v201
	v_mul_u32_u24_e32 v80, s35, v80
	v_add_u32_e32 v80, v80, v176
	v_add_u32_e32 v81, s10, v200
	v_mul_u32_u24_e32 v81, s35, v81
	v_add_u32_e32 v81, v81, v168
	v_mov_b32_e32 v169, v177
	s_add_i32 s8, s20, s15
	s_mov_b32 s9, m0
	s_mov_b32 m0, s8
	s_nop 0
	global_load_lds_dwordx4 v82, s[100:101]
	s_mov_b32 m0, s9
	s_add_u32 s100, s6, s90
	s_addc_u32 s101, s7, s91
	s_add_i32 s8, s21, 16
	s_add_i32 s20, s8, 0x8000
	s_add_i32 s8, s20, s14
	s_mov_b32 s9, m0
	s_mov_b32 m0, s8
	s_nop 0
	global_load_lds_dwordx4 v80, s[100:101]
	s_mov_b32 m0, s9
	s_add_i32 s8, s20, s16
	s_mov_b32 s9, m0
	s_mov_b32 m0, s8
	s_nop 0
	global_load_lds_dwordx4 v81, s[100:101]
	s_mov_b32 m0, s9
	s_cmp_gt_i32 s24, s13
	s_cbranch_scc1 .LBB0_768

; template <int MODE>
; __device__ __forceinline__ void flash_unit(ArgsP A, int l, int b, int h, int qb, unsigned char* lds) {
;     ...
;     auto dma_tile = [&](int t) {
;         const int kr0 = rowbase + 64 * t;
;         const int slot = t % NBUF; const unsigned kb_ = lds0 + slot * KBYTES, vb_ = lds0 + NBUF * KBYTES + slot * VBYTES;
; #pragma unroll
;         for (int i = 0; i < NKI; ++i) { const int piece = wave + 8 * i, p = 64 * piece + lane, key = p / KCH, cs = p % KCH;
;             const int ch = cs ^ (MODE == 1 ? (key & 15) : ((key >> 1) & 7)); const bf16_t* src;
;             if (MODE == 0) src = (ch < 16) ? KVM + (size_t)(kr0 + key) * 1024 + 256 * h + 8 * ch : PROJ + (size_t)(kr0 + key) * INWP + C_KR + 8 * (ch - 16);
;             else if (MODE == 1) src = PROJ + (size_t)(kr0 + key) * INWP + C_DK + 128 * h + 8 * ch;
;             else src = PROJ + (size_t)(kr0 + key) * INWP + C_RK + 64 * h + 8 * ch;
;             glds16(src, (unsigned)__builtin_amdgcn_readfirstlane(kb_ + piece * 1024)); }
; #pragma unroll
;         for (int i = 0; i < 2; ++i) { const int piece = wave + 8 * i, p = 64 * piece + lane, st = p >> 5, key = 8 * (st >> 2) + ((p & 31) >> 2), col = 32 * (st & 3) + 8 * (p & 3); const bf16_t* src;
;             if (MODE == 0) src = KVM + (size_t)(kr0 + key) * 1024 + 256 * h + 128 + col;
;             else if (MODE == 1) src = PROJ + (size_t)(kr0 + key) * INWP + C_DV + 128 * h + col;
;             else src = PROJ + (size_t)(kr0 + key) * INWP + C_RV + 128 * h + col;
;             glds16(src, (unsigned)__builtin_amdgcn_readfirstlane(vb_ + piece * 1024)); }
;         if (MODE == 1) glds4((const int*)A->in[2] + rowbase + 64 * t + lane, (unsigned)__builtin_amdgcn_readfirstlane(lds0 + OFF_EXTRA + slot * 256));
;     };
;     ...
;         if (t + NBUF - 1 < ntile) dma_tile(t + NBUF - 1);
;         if (t <= tlast) {
.LBB0_821:
	s_and_b32 s17, s17, 3
	s_lshl_b32 s20, s17, 14
	s_mov_b32 s22, 16
	s_add_i32 s23, s20, s22
	s_add_u32 s38, s10, s18
	s_addc_u32 s39, s11, 0
	s_add_u32 s38, s38, 0x1980
	s_addc_u32 s39, s39, 0
	s_add_u32 s100, s38, 0x400
	s_addc_u32 s101, s39, 0
	v_add_u32_e32 v66, s24, v126
	v_mul_u32_u24_e32 v66, s35, v66
	v_lshl_add_u32 v66, v114, 1, v66
	v_add_u32_e32 v67, s24, v127
	v_mul_u32_u24_e32 v67, s35, v67
	v_lshl_add_u32 v67, v116, 1, v67
	v_add_u32_e32 v64, s24, v137
	v_mul_u32_u24_e32 v64, s35, v64
	v_add_u32_e32 v64, v64, v176
	v_add_u32_e32 v65, s24, v136
	v_mul_u32_u24_e32 v65, s35, v65
	v_add_u32_e32 v65, v65, v118
	s_add_i32 s20, s23, s31
	s_mov_b32 s21, m0
	s_mov_b32 m0, s20
	s_nop 0
	global_load_lds_dwordx4 v66, s[38:39]
	s_mov_b32 m0, s21
	s_add_i32 s20, s23, s26
	s_mov_b32 s21, m0
	s_mov_b32 m0, s20
	s_nop 0
	global_load_lds_dwordx4 v67, s[38:39]
	s_mov_b32 m0, s21
	s_add_i32 s23, s23, 0x10000
	s_add_i32 s20, s23, s31
	s_mov_b32 s21, m0
	s_mov_b32 m0, s20
	s_nop 0
	global_load_lds_dwordx4 v64, s[100:101]
	s_mov_b32 m0, s21
	s_add_i32 s20, s23, s26
	s_mov_b32 s21, m0
	s_mov_b32 m0, s20
	s_nop 0
	global_load_lds_dwordx4 v65, s[100:101]
	s_mov_b32 m0, s21
	s_mov_b32 s25, s19
	s_lshl_b64 s[20:21], s[24:25], 2
	s_add_u32 s20, s36, s20
	s_addc_u32 s21, s37, s21
	s_lshl_b32 s17, s17, 8
	s_add_i32 s17, s22, s17
	v_lshl_add_u64 v[64:65], v[112:113], 2, s[20:21]
	s_add_i32 s17, s17, 0x20000
	s_mov_b32 s20, m0
	s_mov_b32 m0, s17
	s_nop 0
	global_load_lds_dword v[64:65], off
	s_mov_b32 m0, s20
	s_cmp_gt_u32 s34, s42
	s_cbranch_scc1 .LBB0_810
